# ws_unit phase-4 loops rewritten by hand: in-place K/V register ring, bias folded into MFMA C, batched LDS table reads
# speedup vs baseline: 1.0077x; 1.0077x over previous
.LBB0_206:
	s_andn2_b64 vcc, exec, s[0:1]
	s_cbranch_vccnz .LBB0_247
	v_readlane_b32 s0, v254, 59
	v_readlane_b32 s1, v254, 60
	s_lshl_b32 s0, s0, 7
	v_readlane_b32 s1, v253, 30
	s_or_b32 s0, s0, s1
	s_ashr_i32 s1, s0, 31
	s_lshl_b64 s[0:1], s[0:1], 2
	s_add_u32 s0, s54, s0
	s_addc_u32 s1, s55, s1
	s_add_u32 s6, s0, 0x2d0a6000
	s_addc_u32 s7, s1, 0
	s_bfe_u32 s20, s34, 0x20006
	s_ashr_i32 s21, s34, 8
	s_add_u32 s8, s54, 0x20000000
	s_addc_u32 s9, s55, 0
	s_add_u32 s22, s54, 0x29400000
	s_addc_u32 s23, s55, 0
	s_add_u32 s24, s54, 0x29800000
	s_addc_u32 s25, s55, 0
	s_add_u32 s26, s54, 0x29c00000
	s_addc_u32 s27, s55, 0
	s_add_u32 s28, s54, 0x2d080000
	s_addc_u32 s29, s55, 0
	s_add_u32 s10, s54, 0x28000000
	s_addc_u32 s11, s55, 0
	s_add_u32 s30, s54, 0x29000000
	s_addc_u32 s31, s55, 0
	s_add_u32 s12, s54, 0xa000a00
	s_mul_i32 s0, s20, 0x2980
	s_addc_u32 s13, s55, 0
	s_add_i32 s34, s0, 0
	s_addk_i32 s34, 0x3f94
	s_branch .LBB0_211
.LBB0_210:
	s_and_b64 vcc, exec, s[0:1]
	s_cbranch_vccnz .LBB0_247

.LBB0_215:
	s_or_b64 exec, exec, s[0:1]
	v_readlane_b32 s0, v254, 54
	s_waitcnt vmcnt(0) lgkmcnt(0)
	s_barrier
	v_mov_b32_e32 v0, s0
	ds_read_b32 v0, v0
	s_mov_b64 s[0:1], -1
	s_waitcnt lgkmcnt(0)
	v_cmp_lt_i32_e32 vcc, 63, v0
	v_readfirstlane_b32 s2, v0
	s_cbranch_vccnz .LBB0_210
	s_and_b32 s3, s2, 1
	s_lshl_b32 s0, s3, 2
	s_add_i32 s40, s0, s20
	s_and_b32 s0, s2, -2
	s_add_i32 s0, s0, s21
	s_sub_i32 s41, 63, s0
	s_lshl_b32 s35, s41, 5
	v_readlane_b32 s0, v253, 31
	s_mul_i32 s38, s40, 0x2980
	v_and_b32_e32 v149, 31, v186
	v_bfe_u32 v147, v186, 5, 1
	s_or_b32 s39, s3, s0
	v_or_b32_e32 v150, s35, v149
	s_lshl_b32 s1, s0, 10
	v_add_u32_e32 v151, s1, v150
	s_lshl_b32 s1, s39, 13
	s_add_u32 s16, s28, s1
	s_addc_u32 s17, s29, 0
	v_lshlrev_b32_e32 v152, 2, v150
	global_load_dword v140, v152, s[16:17]
	v_lshlrev_b32_e32 v153, 10, v151
	v_lshl_add_u32 v153, v147, 4, v153
	s_lshl_b32 s1, s40, 7
	s_add_u32 s2, s10, s1
	s_addc_u32 s3, s11, 0
	global_load_dwordx4 v[48:51], v153, s[2:3]
	global_load_dwordx4 v[52:55], v153, s[2:3] offset:32
	global_load_dwordx4 v[56:59], v153, s[2:3] offset:64
	global_load_dwordx4 v[60:63], v153, s[2:3] offset:96
	v_mul_u32_u24_e32 v154, s66, v151
	s_mul_i32 s1, s40, 6
	v_add_u32_e32 v154, s1, v154
	global_load_dword v141, v154, s[12:13] offset:2
	v_and_b32_e32 v144, 63, v186
	v_lshlrev_b32_e32 v144, 4, v144
	v_lshlrev_b32_e32 v145, 5, v149
	v_lshl_add_u32 v145, v147, 4, v145
	s_lshl_b32 s0, s39, 18
	s_add_u32 s42, s22, s0
	s_addc_u32 s43, s23, 0
	s_add_u32 s44, s26, s0
	s_addc_u32 s45, s27, 0
	s_add_u32 s46, s30, s0
	s_addc_u32 s47, s31, 0
	s_add_u32 s48, s24, s0
	s_addc_u32 s49, s25, 0
	s_sub_i32 s14, s41, 16
	s_max_i32 s14, s14, 0
	s_lshl_b32 s0, s14, 12
	s_add_u32 s16, s42, s0
	s_addc_u32 s17, s43, 0
	global_load_dwordx4 v[66:69], v144, s[16:17]
	global_load_dwordx4 v[70:73], v144, s[16:17] offset:1024
	global_load_dwordx4 v[74:77], v144, s[16:17] offset:2048
	global_load_dwordx4 v[78:81], v144, s[16:17] offset:3072
	s_add_u32 s16, s44, s0
	s_addc_u32 s17, s45, 0
	global_load_dwordx4 v[82:85], v145, s[16:17]
	global_load_dwordx4 v[86:89], v145, s[16:17] offset:1024
	global_load_dwordx4 v[90:93], v145, s[16:17] offset:2048
	global_load_dwordx4 v[94:97], v145, s[16:17] offset:3072
	s_add_i32 s1, s14, 1
	s_min_i32 s1, s1, s41
	s_lshl_b32 s0, s1, 12
	s_add_u32 s16, s42, s0
	s_addc_u32 s17, s43, 0
	global_load_dwordx4 v[98:101], v144, s[16:17]
	global_load_dwordx4 v[102:105], v144, s[16:17] offset:1024
	global_load_dwordx4 v[106:109], v144, s[16:17] offset:2048
	global_load_dwordx4 v[110:113], v144, s[16:17] offset:3072
	s_add_u32 s16, s44, s0
	s_addc_u32 s17, s45, 0
	global_load_dwordx4 v[114:117], v145, s[16:17]
	global_load_dwordx4 v[118:121], v145, s[16:17] offset:1024
	global_load_dwordx4 v[122:125], v145, s[16:17] offset:2048
	global_load_dwordx4 v[126:129], v145, s[16:17] offset:3072
	v_lshlrev_b32_e32 v146, 2, v147
	v_sub_u32_e32 v146, v150, v146
	v_add_u32_e32 v146, 5, v146
	v_lshlrev_b32_e32 v146, 2, v146
	v_mov_b32_e32 v157, s38
	v_xor_b32_e32 v148, 32, v190
	v_lshlrev_b32_e32 v148, 2, v148
	v_lshlrev_b32_e32 v156, 13, v151
	v_lshl_add_u32 v156, v147, 4, v156
	v_mov_b32_e32 v138, 0
	v_mov_b32_e32 v202, 0
	v_mov_b32_e32 v203, 0
	v_mov_b32_e32 v204, 0
	v_mov_b32_e32 v205, 0
	v_mov_b32_e32 v206, 0
	v_mov_b32_e32 v207, 0
	v_mov_b32_e32 v208, 0
	v_mov_b32_e32 v209, 0
	v_mov_b32_e32 v210, 0
	v_mov_b32_e32 v211, 0
	v_mov_b32_e32 v212, 0
	v_mov_b32_e32 v213, 0
	v_mov_b32_e32 v214, 0
	v_mov_b32_e32 v215, 0
	v_mov_b32_e32 v216, 0
	v_mov_b32_e32 v217, 0
	v_mov_b32_e32 v218, 0
	v_mov_b32_e32 v219, 0
	v_mov_b32_e32 v220, 0
	v_mov_b32_e32 v221, 0
	v_mov_b32_e32 v222, 0
	v_mov_b32_e32 v223, 0
	v_mov_b32_e32 v224, 0
	v_mov_b32_e32 v225, 0
	v_mov_b32_e32 v226, 0
	v_mov_b32_e32 v227, 0
	v_mov_b32_e32 v228, 0
	v_mov_b32_e32 v229, 0
	v_mov_b32_e32 v230, 0
	v_mov_b32_e32 v231, 0
	v_mov_b32_e32 v232, 0
	v_mov_b32_e32 v233, 0
	s_lshl_b32 s0, s14, 7
	s_sub_i32 s0, 0x2080, s0
	v_add3_u32 v139, s0, v146, v157
	ds_read2_b32 v[32:33], v139 offset0:27 offset1:26
	ds_read2_b32 v[34:35], v139 offset0:25 offset1:24
	ds_read2_b32 v[36:37], v139 offset0:19 offset1:18
	ds_read2_b32 v[38:39], v139 offset0:17 offset1:16
	ds_read2_b32 v[40:41], v139 offset0:11 offset1:10
	ds_read2_b32 v[42:43], v139 offset0:9 offset1:8
	ds_read2_b32 v[44:45], v139 offset0:3 offset1:2
	ds_read2_b32 v[46:47], v139 offset0:1 offset1:0
	s_waitcnt vmcnt(16)
	v_mov_b32_e32 v152, v140
	v_xor_b32_e32 v153, 1, v190
	v_lshlrev_b32_e32 v153, 2, v153
	ds_bpermute_b32 v154, v153, v152
	s_waitcnt lgkmcnt(0)
	v_or_b32_e32 v152, v152, v154
	v_xor_b32_e32 v153, 2, v190
	v_lshlrev_b32_e32 v153, 2, v153
	ds_bpermute_b32 v154, v153, v152
	s_waitcnt lgkmcnt(0)
	v_or_b32_e32 v152, v152, v154
	v_xor_b32_e32 v153, 4, v190
	v_lshlrev_b32_e32 v153, 2, v153
	ds_bpermute_b32 v154, v153, v152
	s_waitcnt lgkmcnt(0)
	v_or_b32_e32 v152, v152, v154
	v_xor_b32_e32 v153, 8, v190
	v_lshlrev_b32_e32 v153, 2, v153
	ds_bpermute_b32 v154, v153, v152
	s_waitcnt lgkmcnt(0)
	v_or_b32_e32 v152, v152, v154
	v_xor_b32_e32 v153, 16, v190
	v_lshlrev_b32_e32 v153, 2, v153
	ds_bpermute_b32 v154, v153, v152
	s_waitcnt lgkmcnt(0)
	v_or_b32_e32 v152, v152, v154
	s_nop 1
	v_readfirstlane_b32 s19, v152
	s_nop 3
	s_mov_b32 s36, s19
	s_ff1_i32_b32 s15, s19
	s_max_i32 s15, s15, 0
	s_add_i32 s0, s19, -1
	s_and_b32 s19, s19, s0
.Lws_wloop:
	s_waitcnt vmcnt(12) lgkmcnt(0)
	v_mfma_f32_32x32x16_bf16 v[32:47], v[66:69], v[48:51], v[32:47]
	v_mfma_f32_32x32x16_bf16 v[32:47], v[70:73], v[52:55], v[32:47]
	v_mfma_f32_32x32x16_bf16 v[32:47], v[74:77], v[56:59], v[32:47]
	v_mfma_f32_32x32x16_bf16 v[32:47], v[78:81], v[60:63], v[32:47]
	s_add_i32 s16, s14, 2
	s_lshl_b32 s17, s16, 12
	s_lshl_b32 s18, s15, 13
	s_cmp_gt_i32 s16, s41
	s_cselect_b32 s17, s18, s17
	s_cselect_b32 s0, s46, s42
	s_cselect_b32 s1, s47, s43
	s_cselect_b32 s2, s48, s44
	s_cselect_b32 s3, s49, s45
	s_cselect_b32 s18, 1, 0
	s_add_u32 s0, s0, s17
	s_addc_u32 s1, s1, 0
	s_add_u32 s2, s2, s17
	s_addc_u32 s3, s3, 0
	global_load_dwordx4 v[66:69], v144, s[0:1]
	global_load_dwordx4 v[70:73], v144, s[0:1] offset:1024
	global_load_dwordx4 v[74:77], v144, s[0:1] offset:2048
	global_load_dwordx4 v[78:81], v144, s[0:1] offset:3072
	v_exp_f32_e32 v32, v32
	v_exp_f32_e32 v33, v33
	v_exp_f32_e32 v34, v34
	v_exp_f32_e32 v35, v35
	v_exp_f32_e32 v36, v36
	v_exp_f32_e32 v37, v37
	v_exp_f32_e32 v38, v38
	v_exp_f32_e32 v39, v39
	v_exp_f32_e32 v40, v40
	v_exp_f32_e32 v41, v41
	v_exp_f32_e32 v42, v42
	v_exp_f32_e32 v43, v43
	v_exp_f32_e32 v44, v44
	v_exp_f32_e32 v45, v45
	v_exp_f32_e32 v46, v46
	v_exp_f32_e32 v47, v47
	v_add_f32_e32 v64, v32, v33
	v_add_f32_e32 v64, v64, v34
	v_add_f32_e32 v64, v64, v35
	v_add_f32_e32 v64, v64, v36
	v_add_f32_e32 v64, v64, v37
	v_add_f32_e32 v64, v64, v38
	v_add_f32_e32 v64, v64, v39
	v_add_f32_e32 v64, v64, v40
	v_add_f32_e32 v64, v64, v41
	v_add_f32_e32 v64, v64, v42
	v_add_f32_e32 v64, v64, v43
	v_add_f32_e32 v64, v64, v44
	v_add_f32_e32 v64, v64, v45
	v_add_f32_e32 v64, v64, v46
	v_add_f32_e32 v64, v64, v47
	v_add_f32_e32 v138, v138, v64
	v_cvt_pk_bf16_f32 v130, v32, v33
	v_cvt_pk_bf16_f32 v131, v34, v35
	v_cvt_pk_bf16_f32 v132, v36, v37
	v_cvt_pk_bf16_f32 v133, v38, v39
	v_cvt_pk_bf16_f32 v134, v40, v41
	v_cvt_pk_bf16_f32 v135, v42, v43
	v_cvt_pk_bf16_f32 v136, v44, v45
	v_cvt_pk_bf16_f32 v137, v46, v47
	s_add_i32 s16, s14, 1
	s_lshl_b32 s17, s16, 7
	s_sub_i32 s17, 0x2080, s17
	s_cmp_le_i32 s16, s41
	s_cselect_b32 s16, 1, 0
	v_add_u32_e32 v152, s17, v146
	v_mad_u32_u24 v139, s16, v152, v157
	ds_read2_b32 v[32:33], v139 offset0:27 offset1:26
	ds_read2_b32 v[34:35], v139 offset0:25 offset1:24
	ds_read2_b32 v[36:37], v139 offset0:19 offset1:18
	ds_read2_b32 v[38:39], v139 offset0:17 offset1:16
	ds_read2_b32 v[40:41], v139 offset0:11 offset1:10
	ds_read2_b32 v[42:43], v139 offset0:9 offset1:8
	ds_read2_b32 v[44:45], v139 offset0:3 offset1:2
	ds_read2_b32 v[46:47], v139 offset0:1 offset1:0
	s_waitcnt vmcnt(12)
	v_mfma_f32_32x32x16_bf16 v[202:217], v[82:85], v[130:133], v[202:217]
	v_mfma_f32_32x32x16_bf16 v[218:233], v[86:89], v[130:133], v[218:233]
	v_mfma_f32_32x32x16_bf16 v[202:217], v[90:93], v[134:137], v[202:217]
	v_mfma_f32_32x32x16_bf16 v[218:233], v[94:97], v[134:137], v[218:233]
	global_load_dwordx4 v[82:85], v145, s[2:3]
	global_load_dwordx4 v[86:89], v145, s[2:3] offset:1024
	global_load_dwordx4 v[90:93], v145, s[2:3] offset:2048
	global_load_dwordx4 v[94:97], v145, s[2:3] offset:3072
	s_waitcnt vmcnt(12) lgkmcnt(0)
	v_mfma_f32_32x32x16_bf16 v[32:47], v[98:101], v[48:51], v[32:47]
	v_mfma_f32_32x32x16_bf16 v[32:47], v[102:105], v[52:55], v[32:47]
	v_mfma_f32_32x32x16_bf16 v[32:47], v[106:109], v[56:59], v[32:47]
	v_mfma_f32_32x32x16_bf16 v[32:47], v[110:113], v[60:63], v[32:47]
	s_add_i32 s16, s14, 3
	s_cmp_le_i32 s16, s41
	s_cselect_b32 s16, 1, 0
	s_or_b32 s16, s16, s18
	s_lshl_b32 s16, s16, 12
	s_add_u32 s0, s0, s16
	s_addc_u32 s1, s1, 0
	s_add_u32 s2, s2, s16
	s_addc_u32 s3, s3, 0
	s_nop 0
	global_load_dwordx4 v[98:101], v144, s[0:1]
	global_load_dwordx4 v[102:105], v144, s[0:1] offset:1024
	global_load_dwordx4 v[106:109], v144, s[0:1] offset:2048
	global_load_dwordx4 v[110:113], v144, s[0:1] offset:3072
	v_exp_f32_e32 v32, v32
	v_exp_f32_e32 v33, v33
	v_exp_f32_e32 v34, v34
	v_exp_f32_e32 v35, v35
	v_exp_f32_e32 v36, v36
	v_exp_f32_e32 v37, v37
	v_exp_f32_e32 v38, v38
	v_exp_f32_e32 v39, v39
	v_exp_f32_e32 v40, v40
	v_exp_f32_e32 v41, v41
	v_exp_f32_e32 v42, v42
	v_exp_f32_e32 v43, v43
	v_exp_f32_e32 v44, v44
	v_exp_f32_e32 v45, v45
	v_exp_f32_e32 v46, v46
	v_exp_f32_e32 v47, v47
	v_add_f32_e32 v64, v32, v33
	v_add_f32_e32 v64, v64, v34
	v_add_f32_e32 v64, v64, v35
	v_add_f32_e32 v64, v64, v36
	v_add_f32_e32 v64, v64, v37
	v_add_f32_e32 v64, v64, v38
	v_add_f32_e32 v64, v64, v39
	v_add_f32_e32 v64, v64, v40
	v_add_f32_e32 v64, v64, v41
	v_add_f32_e32 v64, v64, v42
	v_add_f32_e32 v64, v64, v43
	v_add_f32_e32 v64, v64, v44
	v_add_f32_e32 v64, v64, v45
	v_add_f32_e32 v64, v64, v46
	v_add_f32_e32 v64, v64, v47
	v_add_f32_e32 v138, v138, v64
	v_cvt_pk_bf16_f32 v130, v32, v33
	v_cvt_pk_bf16_f32 v131, v34, v35
	v_cvt_pk_bf16_f32 v132, v36, v37
	v_cvt_pk_bf16_f32 v133, v38, v39
	v_cvt_pk_bf16_f32 v134, v40, v41
	v_cvt_pk_bf16_f32 v135, v42, v43
	v_cvt_pk_bf16_f32 v136, v44, v45
	v_cvt_pk_bf16_f32 v137, v46, v47
	s_add_i32 s16, s14, 2
	s_lshl_b32 s17, s16, 7
	s_sub_i32 s17, 0x2080, s17
	v_add3_u32 v139, s17, v146, v157
	ds_read2_b32 v[32:33], v139 offset0:27 offset1:26
	ds_read2_b32 v[34:35], v139 offset0:25 offset1:24
	ds_read2_b32 v[36:37], v139 offset0:19 offset1:18
	ds_read2_b32 v[38:39], v139 offset0:17 offset1:16
	ds_read2_b32 v[40:41], v139 offset0:11 offset1:10
	ds_read2_b32 v[42:43], v139 offset0:9 offset1:8
	ds_read2_b32 v[44:45], v139 offset0:3 offset1:2
	ds_read2_b32 v[46:47], v139 offset0:1 offset1:0
	s_waitcnt vmcnt(12)
	v_mfma_f32_32x32x16_bf16 v[202:217], v[114:117], v[130:133], v[202:217]
	v_mfma_f32_32x32x16_bf16 v[218:233], v[118:121], v[130:133], v[218:233]
	v_mfma_f32_32x32x16_bf16 v[202:217], v[122:125], v[134:137], v[202:217]
	v_mfma_f32_32x32x16_bf16 v[218:233], v[126:129], v[134:137], v[218:233]
	global_load_dwordx4 v[114:117], v145, s[2:3]
	global_load_dwordx4 v[118:121], v145, s[2:3] offset:1024
	global_load_dwordx4 v[122:125], v145, s[2:3] offset:2048
	global_load_dwordx4 v[126:129], v145, s[2:3] offset:3072
	s_add_i32 s14, s14, 2
	s_cmp_le_i32 s14, s41
	s_cbranch_scc1 .Lws_wloop
	v_and_b32_e32 v152, 0xffff0000, v141
	v_mul_f32_e32 v152, 0xbfb8aa3b, v152
	ds_bpermute_b32 v153, v148, v138
	v_exp_f32_e32 v152, v152
	s_waitcnt lgkmcnt(0)
	v_add_f32_e32 v158, v138, v153
	v_add_f32_e32 v152, 1.0, v152
	v_div_scale_f32 v160, s[16:17], v158, v158, 1.0
	v_rcp_f32_e32 v161, v160
	s_nop 0
	v_fma_f32 v174, -v160, v161, 1.0
	v_fmac_f32_e32 v161, v174, v161
	v_div_scale_f32 v174, vcc, 1.0, v158, 1.0
	v_mul_f32_e32 v175, v174, v161
	v_fma_f32 v176, -v160, v175, v174
	v_fmac_f32_e32 v175, v176, v161
	v_fma_f32 v160, -v160, v175, v174
	v_div_fmas_f32 v160, v160, v161, v175
	v_div_fixup_f32 v159, v160, v158, 1.0
	v_div_scale_f32 v160, s[16:17], v152, v152, 1.0
	v_rcp_f32_e32 v161, v160
	s_nop 0
	v_fma_f32 v174, -v160, v161, 1.0
	v_fmac_f32_e32 v161, v174, v161
	v_div_scale_f32 v174, vcc, 1.0, v152, 1.0
	v_mul_f32_e32 v175, v174, v161
	v_fma_f32 v176, -v160, v175, v174
	v_fmac_f32_e32 v175, v176, v161
	v_fma_f32 v160, -v160, v175, v174
	v_div_fmas_f32 v160, v160, v161, v175
	v_div_fixup_f32 v177, v160, v152, 1.0
	v_cmp_lt_f32_e32 vcc, 0, v158
	s_nop 1
	v_cndmask_b32_e32 v158, 0, v159, vcc
	v_mul_f32_e32 v234, v177, v158
	v_mov_b32_e32 v138, 0
	v_mov_b32_e32 v0, 0
	v_mov_b32_e32 v1, 0
	v_mov_b32_e32 v2, 0
	v_mov_b32_e32 v3, 0
	v_mov_b32_e32 v4, 0
	v_mov_b32_e32 v5, 0
	v_mov_b32_e32 v6, 0
	v_mov_b32_e32 v7, 0
	v_mov_b32_e32 v8, 0
	v_mov_b32_e32 v9, 0
	v_mov_b32_e32 v10, 0
	v_mov_b32_e32 v11, 0
	v_mov_b32_e32 v12, 0
	v_mov_b32_e32 v13, 0
	v_mov_b32_e32 v14, 0
	v_mov_b32_e32 v15, 0
	v_mov_b32_e32 v16, 0
	v_mov_b32_e32 v17, 0
	v_mov_b32_e32 v18, 0
	v_mov_b32_e32 v19, 0
	v_mov_b32_e32 v20, 0
	v_mov_b32_e32 v21, 0
	v_mov_b32_e32 v22, 0
	v_mov_b32_e32 v23, 0
	v_mov_b32_e32 v24, 0
	v_mov_b32_e32 v25, 0
	v_mov_b32_e32 v26, 0
	v_mov_b32_e32 v27, 0
	v_mov_b32_e32 v28, 0
	v_mov_b32_e32 v29, 0
	v_mov_b32_e32 v30, 0
	v_mov_b32_e32 v31, 0
	s_cmp_eq_u32 s36, 0
	s_cbranch_scc1 .Lws_final
	s_mov_b32 s36, s15
	v_bfe_u32 v152, v140, s36, 1
	s_lshl_b32 s16, s36, 8
	s_sub_i32 s16, 0, s16
	v_add_u32_e32 v153, s16, v146
	v_mad_u32_u24 v139, v152, v153, v157
	ds_read2_b32 v[32:33], v139 offset0:27 offset1:26
	ds_read2_b32 v[34:35], v139 offset0:25 offset1:24
	ds_read2_b32 v[36:37], v139 offset0:19 offset1:18
	ds_read2_b32 v[38:39], v139 offset0:17 offset1:16
	ds_read2_b32 v[40:41], v139 offset0:11 offset1:10
	ds_read2_b32 v[42:43], v139 offset0:9 offset1:8
	ds_read2_b32 v[44:45], v139 offset0:3 offset1:2
	ds_read2_b32 v[46:47], v139 offset0:1 offset1:0
.Lws_sloop:
	s_waitcnt vmcnt(12) lgkmcnt(0)
	v_mfma_f32_32x32x16_bf16 v[32:47], v[66:69], v[48:51], v[32:47]
	v_mfma_f32_32x32x16_bf16 v[32:47], v[70:73], v[52:55], v[32:47]
	v_mfma_f32_32x32x16_bf16 v[32:47], v[74:77], v[56:59], v[32:47]
	v_mfma_f32_32x32x16_bf16 v[32:47], v[78:81], v[60:63], v[32:47]
	s_ff1_i32_b32 s18, s19
	s_add_i32 s0, s19, -1
	s_and_b32 s0, s19, s0
	s_cmp_eq_u32 s19, 0
	s_cselect_b32 s18, s36, s18
	s_mov_b32 s19, s0
	s_lshl_b32 s0, s18, 13
	s_add_u32 s2, s48, s0
	s_addc_u32 s3, s49, 0
	s_add_u32 s0, s46, s0
	s_addc_u32 s1, s47, 0
	global_load_dwordx4 v[66:69], v144, s[0:1]
	global_load_dwordx4 v[70:73], v144, s[0:1] offset:1024
	global_load_dwordx4 v[74:77], v144, s[0:1] offset:2048
	global_load_dwordx4 v[78:81], v144, s[0:1] offset:3072
	v_exp_f32_e32 v32, v32
	v_exp_f32_e32 v33, v33
	v_exp_f32_e32 v34, v34
	v_exp_f32_e32 v35, v35
	v_exp_f32_e32 v36, v36
	v_exp_f32_e32 v37, v37
	v_exp_f32_e32 v38, v38
	v_exp_f32_e32 v39, v39
	v_exp_f32_e32 v40, v40
	v_exp_f32_e32 v41, v41
	v_exp_f32_e32 v42, v42
	v_exp_f32_e32 v43, v43
	v_exp_f32_e32 v44, v44
	v_exp_f32_e32 v45, v45
	v_exp_f32_e32 v46, v46
	v_exp_f32_e32 v47, v47
	v_add_f32_e32 v64, v32, v33
	v_add_f32_e32 v64, v64, v34
	v_add_f32_e32 v64, v64, v35
	v_add_f32_e32 v64, v64, v36
	v_add_f32_e32 v64, v64, v37
	v_add_f32_e32 v64, v64, v38
	v_add_f32_e32 v64, v64, v39
	v_add_f32_e32 v64, v64, v40
	v_add_f32_e32 v64, v64, v41
	v_add_f32_e32 v64, v64, v42
	v_add_f32_e32 v64, v64, v43
	v_add_f32_e32 v64, v64, v44
	v_add_f32_e32 v64, v64, v45
	v_add_f32_e32 v64, v64, v46
	v_add_f32_e32 v64, v64, v47
	v_add_f32_e32 v138, v138, v64
	v_cvt_pk_bf16_f32 v130, v32, v33
	v_cvt_pk_bf16_f32 v131, v34, v35
	v_cvt_pk_bf16_f32 v132, v36, v37
	v_cvt_pk_bf16_f32 v133, v38, v39
	v_cvt_pk_bf16_f32 v134, v40, v41
	v_cvt_pk_bf16_f32 v135, v42, v43
	v_cvt_pk_bf16_f32 v136, v44, v45
	v_cvt_pk_bf16_f32 v137, v46, v47
	v_bfe_u32 v152, v140, s36, 1
	s_lshl_b32 s14, s36, 6
	s_lshl_b32 s15, s36, 8
	s_sub_i32 s15, 0xffffff80, s15
	s_cmp_lt_i32 s14, s35
	s_cselect_b32 s14, 1, 0
	v_and_b32_e32 v152, s14, v152
	v_add_u32_e32 v153, s15, v146
	v_mad_u32_u24 v139, v152, v153, v157
	ds_read2_b32 v[32:33], v139 offset0:27 offset1:26
	ds_read2_b32 v[34:35], v139 offset0:25 offset1:24
	ds_read2_b32 v[36:37], v139 offset0:19 offset1:18
	ds_read2_b32 v[38:39], v139 offset0:17 offset1:16
	ds_read2_b32 v[40:41], v139 offset0:11 offset1:10
	ds_read2_b32 v[42:43], v139 offset0:9 offset1:8
	ds_read2_b32 v[44:45], v139 offset0:3 offset1:2
	ds_read2_b32 v[46:47], v139 offset0:1 offset1:0
	s_waitcnt vmcnt(12)
	v_mfma_f32_32x32x16_bf16 v[0:15], v[82:85], v[130:133], v[0:15]
	v_mfma_f32_32x32x16_bf16 v[16:31], v[86:89], v[130:133], v[16:31]
	v_mfma_f32_32x32x16_bf16 v[0:15], v[90:93], v[134:137], v[0:15]
	v_mfma_f32_32x32x16_bf16 v[16:31], v[94:97], v[134:137], v[16:31]
	global_load_dwordx4 v[82:85], v145, s[2:3]
	global_load_dwordx4 v[86:89], v145, s[2:3] offset:1024
	global_load_dwordx4 v[90:93], v145, s[2:3] offset:2048
	global_load_dwordx4 v[94:97], v145, s[2:3] offset:3072
	s_waitcnt vmcnt(12) lgkmcnt(0)
	v_mfma_f32_32x32x16_bf16 v[32:47], v[98:101], v[48:51], v[32:47]
	v_mfma_f32_32x32x16_bf16 v[32:47], v[102:105], v[52:55], v[32:47]
	v_mfma_f32_32x32x16_bf16 v[32:47], v[106:109], v[56:59], v[32:47]
	v_mfma_f32_32x32x16_bf16 v[32:47], v[110:113], v[60:63], v[32:47]
	s_add_u32 s0, s0, 0x1000
	s_addc_u32 s1, s1, 0
	s_add_u32 s2, s2, 0x1000
	s_addc_u32 s3, s3, 0
	s_nop 4
	global_load_dwordx4 v[98:101], v144, s[0:1]
	global_load_dwordx4 v[102:105], v144, s[0:1] offset:1024
	global_load_dwordx4 v[106:109], v144, s[0:1] offset:2048
	global_load_dwordx4 v[110:113], v144, s[0:1] offset:3072
	v_exp_f32_e32 v32, v32
	v_exp_f32_e32 v33, v33
	v_exp_f32_e32 v34, v34
	v_exp_f32_e32 v35, v35
	v_exp_f32_e32 v36, v36
	v_exp_f32_e32 v37, v37
	v_exp_f32_e32 v38, v38
	v_exp_f32_e32 v39, v39
	v_exp_f32_e32 v40, v40
	v_exp_f32_e32 v41, v41
	v_exp_f32_e32 v42, v42
	v_exp_f32_e32 v43, v43
	v_exp_f32_e32 v44, v44
	v_exp_f32_e32 v45, v45
	v_exp_f32_e32 v46, v46
	v_exp_f32_e32 v47, v47
	v_add_f32_e32 v64, v32, v33
	v_add_f32_e32 v64, v64, v34
	v_add_f32_e32 v64, v64, v35
	v_add_f32_e32 v64, v64, v36
	v_add_f32_e32 v64, v64, v37
	v_add_f32_e32 v64, v64, v38
	v_add_f32_e32 v64, v64, v39
	v_add_f32_e32 v64, v64, v40
	v_add_f32_e32 v64, v64, v41
	v_add_f32_e32 v64, v64, v42
	v_add_f32_e32 v64, v64, v43
	v_add_f32_e32 v64, v64, v44
	v_add_f32_e32 v64, v64, v45
	v_add_f32_e32 v64, v64, v46
	v_add_f32_e32 v64, v64, v47
	v_add_f32_e32 v138, v138, v64
	v_cvt_pk_bf16_f32 v130, v32, v33
	v_cvt_pk_bf16_f32 v131, v34, v35
	v_cvt_pk_bf16_f32 v132, v36, v37
	v_cvt_pk_bf16_f32 v133, v38, v39
	v_cvt_pk_bf16_f32 v134, v40, v41
	v_cvt_pk_bf16_f32 v135, v42, v43
	v_cvt_pk_bf16_f32 v136, v44, v45
	v_cvt_pk_bf16_f32 v137, v46, v47
	v_bfe_u32 v152, v140, s18, 1
	s_lshl_b32 s14, s18, 8
	s_sub_i32 s14, 0, s14
	v_add_u32_e32 v153, s14, v146
	v_mad_u32_u24 v139, v152, v153, v157
	ds_read2_b32 v[32:33], v139 offset0:27 offset1:26
	ds_read2_b32 v[34:35], v139 offset0:25 offset1:24
	ds_read2_b32 v[36:37], v139 offset0:19 offset1:18
	ds_read2_b32 v[38:39], v139 offset0:17 offset1:16
	ds_read2_b32 v[40:41], v139 offset0:11 offset1:10
	ds_read2_b32 v[42:43], v139 offset0:9 offset1:8
	ds_read2_b32 v[44:45], v139 offset0:3 offset1:2
	ds_read2_b32 v[46:47], v139 offset0:1 offset1:0
	s_waitcnt vmcnt(12)
	v_mfma_f32_32x32x16_bf16 v[0:15], v[114:117], v[130:133], v[0:15]
	v_mfma_f32_32x32x16_bf16 v[16:31], v[118:121], v[130:133], v[16:31]
	v_mfma_f32_32x32x16_bf16 v[0:15], v[122:125], v[134:137], v[0:15]
	v_mfma_f32_32x32x16_bf16 v[16:31], v[126:129], v[134:137], v[16:31]
	global_load_dwordx4 v[114:117], v145, s[2:3]
	global_load_dwordx4 v[118:121], v145, s[2:3] offset:1024
	global_load_dwordx4 v[122:125], v145, s[2:3] offset:2048
	global_load_dwordx4 v[126:129], v145, s[2:3] offset:3072
	s_cmp_lg_u32 s18, s36
	s_mov_b32 s36, s18
	s_cbranch_scc1 .Lws_sloop
.Lws_final:
	s_lshl_b32 s0, s40, 8
	s_add_u32 s0, s8, s0
	s_addc_u32 s1, s9, 0
	global_load_dwordx4 v[66:69], v156, s[0:1] offset:0
	global_load_dwordx4 v[70:73], v156, s[0:1] offset:32
	global_load_dwordx4 v[74:77], v156, s[0:1] offset:64
	global_load_dwordx4 v[78:81], v156, s[0:1] offset:96
	global_load_dwordx4 v[82:85], v156, s[0:1] offset:128
	global_load_dwordx4 v[86:89], v156, s[0:1] offset:160
	global_load_dwordx4 v[90:93], v156, s[0:1] offset:192
	global_load_dwordx4 v[94:97], v156, s[0:1] offset:224
	v_lshlrev_b32_e32 v152, 16, v141
	v_mul_f32_e32 v152, 0xbfb8aa3b, v152
	ds_bpermute_b32 v153, v148, v138
	v_exp_f32_e32 v152, v152
	s_waitcnt lgkmcnt(0)
	v_add_f32_e32 v158, v138, v153
	v_add_f32_e32 v152, 1.0, v152
	v_div_scale_f32 v160, s[16:17], v158, v158, 1.0
	v_rcp_f32_e32 v161, v160
	s_nop 0
	v_fma_f32 v174, -v160, v161, 1.0
	v_fmac_f32_e32 v161, v174, v161
	v_div_scale_f32 v174, vcc, 1.0, v158, 1.0
	v_mul_f32_e32 v175, v174, v161
	v_fma_f32 v176, -v160, v175, v174
	v_fmac_f32_e32 v175, v176, v161
	v_fma_f32 v160, -v160, v175, v174
	v_div_fmas_f32 v160, v160, v161, v175
	v_div_fixup_f32 v159, v160, v158, 1.0
	v_div_scale_f32 v160, s[16:17], v152, v152, 1.0
	v_rcp_f32_e32 v161, v160
	s_nop 0
	v_fma_f32 v174, -v160, v161, 1.0
	v_fmac_f32_e32 v161, v174, v161
	v_div_scale_f32 v174, vcc, 1.0, v152, 1.0
	v_mul_f32_e32 v175, v174, v161
	v_fma_f32 v176, -v160, v175, v174
	v_fmac_f32_e32 v175, v176, v161
	v_fma_f32 v160, -v160, v175, v174
	v_div_fmas_f32 v160, v160, v161, v175
	v_div_fixup_f32 v177, v160, v152, 1.0
	v_cmp_lt_f32_e32 vcc, 0, v158
	s_nop 1
	v_cndmask_b32_e32 v158, 0, v159, vcc
	v_mul_f32_e32 v236, v177, v158
	s_waitcnt vmcnt(7)
	v_pk_fma_f32 v[66:67], v[202:203], v[234:235], v[66:67] op_sel_hi:[1,0,1]
	v_pk_fma_f32 v[68:69], v[204:205], v[234:235], v[68:69] op_sel_hi:[1,0,1]
	v_pk_fma_f32 v[66:67], v[0:1], v[236:237], v[66:67] op_sel_hi:[1,0,1]
	v_pk_fma_f32 v[68:69], v[2:3], v[236:237], v[68:69] op_sel_hi:[1,0,1]
	s_waitcnt vmcnt(6)
	v_pk_fma_f32 v[70:71], v[206:207], v[234:235], v[70:71] op_sel_hi:[1,0,1]
	v_pk_fma_f32 v[72:73], v[208:209], v[234:235], v[72:73] op_sel_hi:[1,0,1]
	v_pk_fma_f32 v[70:71], v[4:5], v[236:237], v[70:71] op_sel_hi:[1,0,1]
	v_pk_fma_f32 v[72:73], v[6:7], v[236:237], v[72:73] op_sel_hi:[1,0,1]
	s_waitcnt vmcnt(5)
	v_pk_fma_f32 v[74:75], v[210:211], v[234:235], v[74:75] op_sel_hi:[1,0,1]
	v_pk_fma_f32 v[76:77], v[212:213], v[234:235], v[76:77] op_sel_hi:[1,0,1]
	v_pk_fma_f32 v[74:75], v[8:9], v[236:237], v[74:75] op_sel_hi:[1,0,1]
	v_pk_fma_f32 v[76:77], v[10:11], v[236:237], v[76:77] op_sel_hi:[1,0,1]
	s_waitcnt vmcnt(4)
	v_pk_fma_f32 v[78:79], v[214:215], v[234:235], v[78:79] op_sel_hi:[1,0,1]
	v_pk_fma_f32 v[80:81], v[216:217], v[234:235], v[80:81] op_sel_hi:[1,0,1]
	v_pk_fma_f32 v[78:79], v[12:13], v[236:237], v[78:79] op_sel_hi:[1,0,1]
	v_pk_fma_f32 v[80:81], v[14:15], v[236:237], v[80:81] op_sel_hi:[1,0,1]
	s_waitcnt vmcnt(3)
	v_pk_fma_f32 v[82:83], v[218:219], v[234:235], v[82:83] op_sel_hi:[1,0,1]
	v_pk_fma_f32 v[84:85], v[220:221], v[234:235], v[84:85] op_sel_hi:[1,0,1]
	v_pk_fma_f32 v[82:83], v[16:17], v[236:237], v[82:83] op_sel_hi:[1,0,1]
	v_pk_fma_f32 v[84:85], v[18:19], v[236:237], v[84:85] op_sel_hi:[1,0,1]
	s_waitcnt vmcnt(2)
	v_pk_fma_f32 v[86:87], v[222:223], v[234:235], v[86:87] op_sel_hi:[1,0,1]
	v_pk_fma_f32 v[88:89], v[224:225], v[234:235], v[88:89] op_sel_hi:[1,0,1]
	v_pk_fma_f32 v[86:87], v[20:21], v[236:237], v[86:87] op_sel_hi:[1,0,1]
	v_pk_fma_f32 v[88:89], v[22:23], v[236:237], v[88:89] op_sel_hi:[1,0,1]
	s_waitcnt vmcnt(1)
	v_pk_fma_f32 v[90:91], v[226:227], v[234:235], v[90:91] op_sel_hi:[1,0,1]
	v_pk_fma_f32 v[92:93], v[228:229], v[234:235], v[92:93] op_sel_hi:[1,0,1]
	v_pk_fma_f32 v[90:91], v[24:25], v[236:237], v[90:91] op_sel_hi:[1,0,1]
	v_pk_fma_f32 v[92:93], v[26:27], v[236:237], v[92:93] op_sel_hi:[1,0,1]
	s_waitcnt vmcnt(0)
	v_pk_fma_f32 v[94:95], v[230:231], v[234:235], v[94:95] op_sel_hi:[1,0,1]
	v_pk_fma_f32 v[96:97], v[232:233], v[234:235], v[96:97] op_sel_hi:[1,0,1]
	v_pk_fma_f32 v[94:95], v[28:29], v[236:237], v[94:95] op_sel_hi:[1,0,1]
	v_pk_fma_f32 v[96:97], v[30:31], v[236:237], v[96:97] op_sel_hi:[1,0,1]
	global_store_dwordx4 v156, v[66:69], s[0:1] offset:0
	global_store_dwordx4 v156, v[70:73], s[0:1] offset:32
	global_store_dwordx4 v156, v[74:77], s[0:1] offset:64
	global_store_dwordx4 v156, v[78:81], s[0:1] offset:96
	global_store_dwordx4 v156, v[82:85], s[0:1] offset:128
	global_store_dwordx4 v156, v[86:89], s[0:1] offset:160
	global_store_dwordx4 v156, v[90:93], s[0:1] offset:192
	global_store_dwordx4 v156, v[94:97], s[0:1] offset:224
	v_readlane_b32 s35, v255, 1
	s_mov_b64 s[0:1], 0
	s_barrier
	s_branch .LBB0_210
